# attention softmax row-max: drop redundant IEEE canonicalising v_max (max3 tree, interleaved qk chains, 2 permlane swaps each)
# speedup vs baseline: 1.0188x; 1.0077x over previous
; __device__ __forceinline__ float xmax16(float m) { const auto r = __builtin_amdgcn_permlane16_swap(__float_as_uint(m), __float_as_uint(m), false, false); return fmaxf(__uint_as_float(r[0]), __uint_as_float(r[1])); }
; __device__ __forceinline__ float xmax32(float m) { const auto r = __builtin_amdgcn_permlane32_swap(__float_as_uint(m), __float_as_uint(m), false, false); return fmaxf(__uint_as_float(r[0]), __uint_as_float(r[1])); }
; __device__ __forceinline__ void attn_unit(const Params& P, LAS unsigned char* lds, int bh, int qb) {
;     ...
;             float mx[2];
; #pragma unroll
;             for (int qk = 0; qk < 2; ++qk) { float m_ = fmaxf(fmaxf(s[0][qk][0], s[0][qk][1]), fmaxf(s[0][qk][2], s[0][qk][3]));
; #pragma unroll
;                 for (int kvb = 1; kvb < 4; ++kvb) m_ = fmaxf(m_, fmaxf(fmaxf(s[kvb][qk][0], s[kvb][qk][1]), fmaxf(s[kvb][qk][2], s[kvb][qk][3])));
;                 m_ = xmax16(m_); m_ = xmax32(m_); mx[qk] = m_; }
;             if (t == 0 || __any((mx[0] > AT_THR) || (mx[1] > AT_THR))) {
.LBB0_645:
	v_max3_f32 v207, v164, v165, v166
	v_max3_f32 v206, v148, v149, v150
	v_max3_f32 v207, v207, v167, v160
	v_max3_f32 v206, v206, v151, v144
	v_max3_f32 v207, v207, v161, v162
	v_max3_f32 v206, v206, v145, v146
	v_max3_f32 v207, v207, v163, v156
	v_max3_f32 v206, v206, v147, v140
	v_max3_f32 v207, v207, v157, v158
	v_max3_f32 v206, v206, v141, v142
	v_max3_f32 v207, v207, v159, v152
	v_max3_f32 v206, v206, v143, v136
	v_max3_f32 v207, v207, v153, v154
	v_max3_f32 v206, v206, v137, v138
	v_max_f32_e32 v207, v207, v155
	v_max_f32_e32 v206, v206, v139
	v_mov_b32_e32 v224, v207
	v_mov_b32_e32 v225, v206
	s_nop 0
	v_permlane16_swap_b32_e32 v207, v224
	v_permlane16_swap_b32_e32 v206, v225
	v_max_f32_e32 v207, v207, v224
	v_max_f32_e32 v206, v206, v225
	v_mov_b32_e32 v224, v207
	v_mov_b32_e32 v225, v206
	s_nop 0
	v_permlane32_swap_b32_e32 v207, v224
	v_permlane32_swap_b32_e32 v206, v225
	v_max_f32_e32 v207, v207, v224
	v_max_f32_e32 v206, v206, v225
	s_cmp_eq_u32 s85, 0
	s_cselect_b64 s[0:1], -1, 0
	s_mov_b64 s[54:55], -1
	s_and_b64 vcc, exec, s[0:1]
	v_mov_b32_e32 v224, v206
	s_cbranch_vccnz .LBB0_648
	v_max_f32_e32 v207, v207, v207
	v_max_f32_e32 v225, v207, v224
	s_mov_b32 s53, 0x41000000
	v_cmp_lt_f32_e32 vcc, s53, v225
	s_cbranch_vccz .LBB0_656
	v_max_f32_e32 v207, 0, v207
